# previous stack + attention bmax2: 32 uniform bias loads issued together + max tree instead of ~18 serialized load/wait round trips per unit
# baseline (speedup 1.0000x reference)
; __device__ __forceinline__ void attn_phase(const Params& p, int e, char* lds) {
;     ...
;     float bmax2 = -1e30f;
; #pragma unroll 4
;     for (int bk = 0; bk < 32; ++bk) bmax2 = fmaxf(bmax2, p.rel_bias[bk * 4 + h] * LOG2E);
;     const unsigned* kmx = (const unsigned*)(p.ws + WS_KMX) + e * 128 + b * 8 + h * 2;
;     const float mbK0 = __uint_as_float(__builtin_amdgcn_readfirstlane(__float_as_uint(C1 * 1.01f * __builtin_sqrtf(2.0f * __uint_as_float(kmx[0])))));
;     const float mbK1 = __uint_as_float(__builtin_amdgcn_readfirstlane(__float_as_uint(C1 * 1.01f * __builtin_sqrtf(2.0f * __uint_as_float(kmx[1])))));
;     bmax2 = __uint_as_float(__builtin_amdgcn_readfirstlane(__float_as_uint(bmax2)));
.LBB0_266:
	v_readlane_b32 s80, v252, 30
	v_readlane_b32 s81, v252, 31
	v_readlane_b32 s82, v252, 32
	v_readlane_b32 s83, v252, 33
	v_readlane_b32 s84, v252, 34
	v_readlane_b32 s85, v252, 35
	v_readlane_b32 s86, v252, 36
	v_readlane_b32 s87, v252, 37
	v_readlane_b32 s88, v252, 38
	v_readlane_b32 s89, v252, 39
	v_readlane_b32 s90, v252, 40
	v_readlane_b32 s91, v252, 41
	v_readlane_b32 s92, v252, 42
	v_readlane_b32 s93, v252, 43
	v_readlane_b32 s94, v252, 44
	v_readlane_b32 s95, v252, 45
	s_nop 3
	s_lshl_b32 s0, s44, 2
	s_add_u32 s20, s82, s0
	s_addc_u32 s21, s83, 0
	global_load_dword v1, v144, s[20:21]
	global_load_dword v2, v144, s[20:21] offset:16
	global_load_dword v3, v144, s[20:21] offset:32
	global_load_dword v4, v144, s[20:21] offset:48
	global_load_dword v5, v144, s[20:21] offset:64
	global_load_dword v6, v144, s[20:21] offset:80
	global_load_dword v7, v144, s[20:21] offset:96
	global_load_dword v8, v144, s[20:21] offset:112
	global_load_dword v9, v144, s[20:21] offset:128
	global_load_dword v10, v144, s[20:21] offset:144
	global_load_dword v11, v144, s[20:21] offset:160
	global_load_dword v12, v144, s[20:21] offset:176
	global_load_dword v13, v144, s[20:21] offset:192
	global_load_dword v14, v144, s[20:21] offset:208
	global_load_dword v15, v144, s[20:21] offset:224
	global_load_dword v16, v144, s[20:21] offset:240
	global_load_dword v17, v144, s[20:21] offset:256
	global_load_dword v18, v144, s[20:21] offset:272
	global_load_dword v19, v144, s[20:21] offset:288
	global_load_dword v20, v144, s[20:21] offset:304
	global_load_dword v21, v144, s[20:21] offset:320
	global_load_dword v22, v144, s[20:21] offset:336
	global_load_dword v23, v144, s[20:21] offset:352
	global_load_dword v24, v144, s[20:21] offset:368
	global_load_dword v25, v144, s[20:21] offset:384
	global_load_dword v26, v144, s[20:21] offset:400
	global_load_dword v27, v144, s[20:21] offset:416
	global_load_dword v28, v144, s[20:21] offset:432
	global_load_dword v29, v144, s[20:21] offset:448
	global_load_dword v30, v144, s[20:21] offset:464
	global_load_dword v31, v144, s[20:21] offset:480
	global_load_dword v32, v144, s[20:21] offset:496
	s_waitcnt vmcnt(0)
	v_max3_f32 v1, v1, v2, v3
	v_max3_f32 v4, v4, v5, v6
	v_max3_f32 v7, v7, v8, v9
	v_max3_f32 v10, v10, v11, v12
	v_max3_f32 v13, v13, v14, v15
	v_max3_f32 v16, v16, v17, v18
	v_max3_f32 v19, v19, v20, v21
	v_max3_f32 v22, v22, v23, v24
	v_max3_f32 v25, v25, v26, v27
	v_max3_f32 v28, v28, v29, v30
	v_max_f32_e32 v31, v31, v32
	v_max3_f32 v1, v1, v4, v7
	v_max3_f32 v10, v10, v13, v16
	v_max3_f32 v19, v19, v22, v25
	v_max_f32_e32 v28, v28, v31
	v_max3_f32 v1, v1, v10, v19
	v_max_f32_e32 v1, v1, v28
	v_mul_f32_e32 v0, 0x3fb8aa3b, v1
	v_max_f32_e32 v0, 0xf149f2ca, v0
